# P5: LoRA outputs WL/AL/GL moved to LDS offset 0.. (no longer alias the weight image): one barrier per head removed, 48 address adds per wave-head folded into ds offset immediates; on top of all13
# speedup vs baseline: 1.0039x; 1.0039x over previous
; #define LAS __attribute__((address_space(3)))
; #define LBAR() asm volatile("s_waitcnt lgkmcnt(0)\n\ts_barrier" ::: "memory")
; #define TSUB(k) do { } while (0)
; __device__ __forceinline__ void rwkv_chunk_group(Frame& F, int bc, unsigned long long& tsub) {
;     ...
;         asm volatile("s_waitcnt vmcnt(0)" ::: "memory"); LBAR();
;         f32x4 aw[2], aa[2], ag[2];
; #pragma unroll
;         for (int q = 0; q < 2; ++q) { const int n0 = 16 * ((2 * w + q) & 3); aw[q] = Z4; aa[q] = Z4; ag[q] = Z4;
;             const LAS unsigned char* wp = L + L_LWA + (n0 + fr) * 128 + fq * 16; const LAS unsigned char* gp = L + L_LG + (n0 + fr) * 64 + fq * 16;
; #pragma unroll
;             for (int k = 0; k < 2; ++k) { aw[q] = __builtin_amdgcn_mfma_f32_16x16x32_bf16(xw[k], *(const LAS bf16x8*)(wp + k * 64), aw[q], 0, 0, 0); aa[q] = __builtin_amdgcn_mfma_f32_16x16x32_bf16(xa[k], *(const LAS bf16x8*)(wp + 8192 + k * 64), aa[q], 0, 0, 0); }
; #pragma unroll
;             for (int k = 0; k < 5; ++k) ag[q] = __builtin_amdgcn_mfma_f32_16x16x32_bf16(xg[k], *(const LAS bf16x8*)(gp + k * 4096), ag[q], 0, 0, 0);
;         }
;         LBAR();
; #pragma unroll
;         for (int q = 0; q < 2; ++q) { const int tw = 2 * w + q, m0 = 16 * (tw >> 2), n0 = 16 * (tw & 3);
; #pragma unroll
;             for (int v = 0; v < 4; ++v) { const int t = m0 + 4 * fq + v, cc = n0 + fr;
;                 *(LAS float*)(L + L_WL + (t * 65 + cc) * 4) = aw[q][v]; *(LAS float*)(L + L_AL + (t * 65 + cc) * 4) = aa[q][v]; *(LAS float*)(L + L_GL + (t * 65 + cc) * 4) = ag[q][v]; } }
;         LBAR();
;     }
;     TSUB(1);
;     {
;         const int gc = h * 64 + ch;
;         const float mur = mu[gc], muk = mu[512 + gc], muv = mu[1024 + gc];
;         const float w0 = (PRM + 2048)[gc], a0 = (PRM + 2560)[gc], k_k = (PRM + 3072)[gc], k_a = (PRM + 3584)[gc], r_k = (PRM + 4096)[gc];
.LBB0_1412:
	s_waitcnt vmcnt(8)
	v_perm_b32 v160, v203, v202, s5
	v_perm_b32 v161, v216, v215, s5
	v_perm_b32 v166, v204, v203, s5
	v_perm_b32 v167, v217, v216, s5
	v_perm_b32 v168, v206, v205, s5
	v_perm_b32 v169, v219, v218, s5
	v_perm_b32 v170, v212, v207, s5
	v_perm_b32 v171, v221, v220, s5
	v_perm_b32 v165, v214, v213, s5
	v_perm_b32 v172, v223, v222, s5
	v_readlane_b32 s98, v254, 2
	v_readlane_b32 s100, v254, 20
	v_readlane_b32 s101, v254, 21
	s_add_i32 s98, s98, s12
	s_lshl_b32 s98, s98, 6
	s_and_b32 s98, s98, 0x1c0
	v_add_lshl_u32 v238, v208, s98, 2
	v_mov_b32_e32 v239, 0
	s_nop 0
	v_lshl_add_u64 v[232:233], s[100:101], 0, v[238:239]
	s_mov_b64 s[100:101], 0x2000
	v_lshl_add_u64 v[234:235], v[232:233], 0, s[100:101]
	s_mov_b64 s[100:101], 0x3800
	v_lshl_add_u64 v[236:237], v[232:233], 0, s[100:101]
	global_load_dword v224, v[232:233], off
	global_load_dword v225, v[232:233], off offset:2048
	global_load_dword v226, v[234:235], off offset:-4096
	global_load_dword v227, v[234:235], off
	global_load_dword v228, v[234:235], off offset:2048
	global_load_dword v229, v[236:237], off offset:-2048
	global_load_dword v230, v[236:237], off
	global_load_dword v231, v[236:237], off offset:2048
	s_waitcnt lgkmcnt(0)
	s_barrier
	v_xor_b32_e32 v102, 64, v137
	v_xor_b32_e32 v103, 64, v139
	ds_read_b128 v[36:39], v137
	ds_read_b128 v[76:79], v139
	ds_read_b128 v[98:101], v102
	ds_read_b128 v[174:177], v103
	ds_read_b128 v[40:43], v137 offset:8192
	ds_read_b128 v[80:83], v139 offset:8192
	ds_read_b128 v[178:181], v102 offset:8192
	ds_read_b128 v[182:185], v103 offset:8192
	ds_read_b128 v[44:47], v138
	ds_read_b128 v[84:87], v140
	ds_read_b128 v[186:189], v138 offset:4096
	ds_read_b128 v[232:235], v140 offset:4096
	ds_read_b128 v[236:239], v138 offset:8192
	ds_read_b128 v[240:243], v140 offset:8192
	ds_read_b128 v[244:247], v138 offset:12288
	s_waitcnt lgkmcnt(14)
	v_mfma_f32_16x16x32_bf16 v[36:39], v[0:3], v[36:39], 0
	ds_read_b128 v[248:251], v140 offset:12288

; #define LAS __attribute__((address_space(3)))
; #define LBAR() asm volatile("s_waitcnt lgkmcnt(0)\n\ts_barrier" ::: "memory")
; __device__ __forceinline__ void rwkv_chunk_group(Frame& F, int bc, unsigned long long& tsub) {
;     ...
;     const int h = (hh + F.vcu) & (RW_H - 1), hnext = (hh + 1 + F.vcu) & (RW_H - 1);
;     const int item = (b * RW_H + h) * NCH + c;
;     {
;         asm volatile("s_waitcnt vmcnt(0)" ::: "memory"); LBAR();
;         f32x4 aw[2], aa[2], ag[2];
; #pragma unroll
;         for (int q = 0; q < 2; ++q) { const int n0 = 16 * ((2 * w + q) & 3); aw[q] = Z4; aa[q] = Z4; ag[q] = Z4;
;             const LAS unsigned char* wp = L + L_LWA + (n0 + fr) * 128 + fq * 16; const LAS unsigned char* gp = L + L_LG + (n0 + fr) * 64 + fq * 16;
; #pragma unroll
;             for (int k = 0; k < 2; ++k) { aw[q] = __builtin_amdgcn_mfma_f32_16x16x32_bf16(xw[k], *(const LAS bf16x8*)(wp + k * 64), aw[q], 0, 0, 0); aa[q] = __builtin_amdgcn_mfma_f32_16x16x32_bf16(xa[k], *(const LAS bf16x8*)(wp + 8192 + k * 64), aa[q], 0, 0, 0); }
; #pragma unroll
;             for (int k = 0; k < 5; ++k) ag[q] = __builtin_amdgcn_mfma_f32_16x16x32_bf16(xg[k], *(const LAS bf16x8*)(gp + k * 4096), ag[q], 0, 0, 0);
	s_mov_b32 s68, s12
	s_waitcnt lgkmcnt(14)
	v_mfma_f32_16x16x32_bf16 v[76:79], v[0:3], v[76:79], 0
	ds_read_b128 v[88:91], v138 offset:16384
	v_readlane_b32 s12, v254, 2
	s_add_i32 s14, s68, s12
	s_waitcnt lgkmcnt(14)
	v_mfma_f32_16x16x32_bf16 v[36:39], v[4:7], v[98:101], v[36:39]
	ds_read_b128 v[98:101], v140 offset:16384
	s_lshl_b32 s14, s14, 6
	s_waitcnt lgkmcnt(14)
	v_mfma_f32_16x16x32_bf16 v[76:79], v[4:7], v[174:177], v[76:79]
	s_and_b32 s14, s14, 0x1c0
	s_waitcnt lgkmcnt(13)
	v_mfma_f32_16x16x32_bf16 v[40:43], v[8:11], v[40:43], 0
	s_add_i32 s66, s11, s14
	s_waitcnt lgkmcnt(12)
	v_mfma_f32_16x16x32_bf16 v[80:83], v[8:11], v[80:83], 0

; #define LAS __attribute__((address_space(3)))
; __device__ __forceinline__ void rwkv_chunk_group(Frame& F, int bc, unsigned long long& tsub) {
;     ...
;             for (int k = 0; k < 2; ++k) { aw[q] = __builtin_amdgcn_mfma_f32_16x16x32_bf16(xw[k], *(const LAS bf16x8*)(wp + k * 64), aw[q], 0, 0, 0); aa[q] = __builtin_amdgcn_mfma_f32_16x16x32_bf16(xa[k], *(const LAS bf16x8*)(wp + 8192 + k * 64), aa[q], 0, 0, 0); }
	s_waitcnt lgkmcnt(11)
	v_mfma_f32_16x16x32_bf16 v[40:43], v[12:15], v[178:181], v[40:43]

; #define LAS __attribute__((address_space(3)))
; #define LBAR() asm volatile("s_waitcnt lgkmcnt(0)\n\ts_barrier" ::: "memory")
; __device__ __forceinline__ void rwkv_chunk_group(Frame& F, int bc, unsigned long long& tsub) {
;     ...
;     const int h = (hh + F.vcu) & (RW_H - 1), hnext = (hh + 1 + F.vcu) & (RW_H - 1);
;     const int item = (b * RW_H + h) * NCH + c;
;     {
;         asm volatile("s_waitcnt vmcnt(0)" ::: "memory"); LBAR();
;         f32x4 aw[2], aa[2], ag[2];
; #pragma unroll
;         for (int q = 0; q < 2; ++q) { const int n0 = 16 * ((2 * w + q) & 3); aw[q] = Z4; aa[q] = Z4; ag[q] = Z4;
;             const LAS unsigned char* wp = L + L_LWA + (n0 + fr) * 128 + fq * 16; const LAS unsigned char* gp = L + L_LG + (n0 + fr) * 64 + fq * 16;
; #pragma unroll
;             for (int k = 0; k < 2; ++k) { aw[q] = __builtin_amdgcn_mfma_f32_16x16x32_bf16(xw[k], *(const LAS bf16x8*)(wp + k * 64), aw[q], 0, 0, 0); aa[q] = __builtin_amdgcn_mfma_f32_16x16x32_bf16(xa[k], *(const LAS bf16x8*)(wp + 8192 + k * 64), aa[q], 0, 0, 0); }
; #pragma unroll
;             for (int k = 0; k < 5; ++k) ag[q] = __builtin_amdgcn_mfma_f32_16x16x32_bf16(xg[k], *(const LAS bf16x8*)(gp + k * 4096), ag[q], 0, 0, 0);
	s_waitcnt lgkmcnt(10)
	v_mfma_f32_16x16x32_bf16 v[80:83], v[12:15], v[182:185], v[80:83]
	s_mov_b32 s64, s12
	s_waitcnt lgkmcnt(9)
	v_mfma_f32_16x16x32_bf16 v[44:47], v[16:19], v[44:47], 0
	s_add_i32 s12, s68, 1
	s_waitcnt lgkmcnt(8)
	v_mfma_f32_16x16x32_bf16 v[84:87], v[16:19], v[84:87], 0
	s_add_i32 s13, s12, s64
	s_waitcnt lgkmcnt(7)
	v_mfma_f32_16x16x32_bf16 v[44:47], v[20:23], v[186:189], v[44:47]

; #define LAS __attribute__((address_space(3)))
; __device__ __forceinline__ void rwkv_chunk_group(Frame& F, int bc, unsigned long long& tsub) {
;     ...
;             for (int k = 0; k < 5; ++k) ag[q] = __builtin_amdgcn_mfma_f32_16x16x32_bf16(xg[k], *(const LAS bf16x8*)(gp + k * 4096), ag[q], 0, 0, 0);
	s_waitcnt lgkmcnt(6)
	v_mfma_f32_16x16x32_bf16 v[84:87], v[20:23], v[232:235], v[84:87]

; #define LAS __attribute__((address_space(3)))
; __device__ __forceinline__ void rwkv_chunk_group(Frame& F, int bc, unsigned long long& tsub) {
;     ...
;             for (int k = 0; k < 5; ++k) ag[q] = __builtin_amdgcn_mfma_f32_16x16x32_bf16(xg[k], *(const LAS bf16x8*)(gp + k * 4096), ag[q], 0, 0, 0);
	s_waitcnt lgkmcnt(5)
	v_mfma_f32_16x16x32_bf16 v[44:47], v[24:27], v[236:239], v[44:47]

; #define LAS __attribute__((address_space(3)))
; __device__ __forceinline__ void rwkv_chunk_group(Frame& F, int bc, unsigned long long& tsub) {
;     ...
;             for (int k = 0; k < 5; ++k) ag[q] = __builtin_amdgcn_mfma_f32_16x16x32_bf16(xg[k], *(const LAS bf16x8*)(gp + k * 4096), ag[q], 0, 0, 0);
	s_waitcnt lgkmcnt(4)
	v_mfma_f32_16x16x32_bf16 v[84:87], v[24:27], v[240:243], v[84:87]

; #define LAS __attribute__((address_space(3)))
; #define LBAR() asm volatile("s_waitcnt lgkmcnt(0)\n\ts_barrier" ::: "memory")
; __device__ __forceinline__ void rwkv_chunk_group(Frame& F, int bc, unsigned long long& tsub) {
;     ...
;         for (int q = 0; q < 2; ++q) { const int n0 = 16 * ((2 * w + q) & 3); aw[q] = Z4; aa[q] = Z4; ag[q] = Z4;
;             const LAS unsigned char* wp = L + L_LWA + (n0 + fr) * 128 + fq * 16; const LAS unsigned char* gp = L + L_LG + (n0 + fr) * 64 + fq * 16;
; #pragma unroll
;             for (int k = 0; k < 2; ++k) { aw[q] = __builtin_amdgcn_mfma_f32_16x16x32_bf16(xw[k], *(const LAS bf16x8*)(wp + k * 64), aw[q], 0, 0, 0); aa[q] = __builtin_amdgcn_mfma_f32_16x16x32_bf16(xa[k], *(const LAS bf16x8*)(wp + 8192 + k * 64), aa[q], 0, 0, 0); }
; #pragma unroll
;             for (int k = 0; k < 5; ++k) ag[q] = __builtin_amdgcn_mfma_f32_16x16x32_bf16(xg[k], *(const LAS bf16x8*)(gp + k * 4096), ag[q], 0, 0, 0);
;         }
;         LBAR();
; #pragma unroll
;         for (int q = 0; q < 2; ++q) { const int tw = 2 * w + q, m0 = 16 * (tw >> 2), n0 = 16 * (tw & 3);
; #pragma unroll
;             for (int v = 0; v < 4; ++v) { const int t = m0 + 4 * fq + v, cc = n0 + fr;
;                 *(LAS float*)(L + L_WL + (t * 65 + cc) * 4) = aw[q][v]; *(LAS float*)(L + L_AL + (t * 65 + cc) * 4) = aa[q][v]; *(LAS float*)(L + L_GL + (t * 65 + cc) * 4) = ag[q][v]; } }
	s_waitcnt lgkmcnt(3)
	v_mfma_f32_16x16x32_bf16 v[44:47], v[28:31], v[244:247], v[44:47]
	v_lshlrev_b32_e32 v197, 16, v162
	s_waitcnt lgkmcnt(2)
	v_mfma_f32_16x16x32_bf16 v[84:87], v[28:31], v[248:251], v[84:87]
	v_and_b32_e32 v199, 0xffff0000, v172
	s_waitcnt lgkmcnt(1)
	v_mfma_f32_16x16x32_bf16 v[44:47], v[32:35], v[88:91], v[44:47]
	s_ashr_i32 s67, s66, 31
	s_waitcnt lgkmcnt(0)
	v_mfma_f32_16x16x32_bf16 v[84:87], v[32:35], v[98:101], v[84:87]
	s_and_b32 s13, s13, 7
	s_nop 7
	s_nop 7


; #define LAS __attribute__((address_space(3)))
; __device__ __forceinline__ void rwkv_chunk_group(Frame& F, int bc, unsigned long long& tsub) {
;     ...
;         for (int q = 0; q < 2; ++q) { const int tw = 2 * w + q, m0 = 16 * (tw >> 2), n0 = 16 * (tw & 3);
; #pragma unroll
;             for (int v = 0; v < 4; ++v) { const int t = m0 + 4 * fq + v, cc = n0 + fr;
;                 *(LAS float*)(L + L_WL + (t * 65 + cc) * 4) = aw[q][v]; *(LAS float*)(L + L_AL + (t * 65 + cc) * 4) = aa[q][v]; *(LAS float*)(L + L_GL + (t * 65 + cc) * 4) = ag[q][v]; } }
	ds_write_b32 v111, v36

; #define LAS __attribute__((address_space(3)))
; __device__ __forceinline__ void rwkv_chunk_group(Frame& F, int bc, unsigned long long& tsub) {
;     ...
;         for (int q = 0; q < 2; ++q) { const int tw = 2 * w + q, m0 = 16 * (tw >> 2), n0 = 16 * (tw & 3);
; #pragma unroll
;             for (int v = 0; v < 4; ++v) { const int t = m0 + 4 * fq + v, cc = n0 + fr;
;                 *(LAS float*)(L + L_WL + (t * 65 + cc) * 4) = aw[q][v]; *(LAS float*)(L + L_AL + (t * 65 + cc) * 4) = aa[q][v]; *(LAS float*)(L + L_GL + (t * 65 + cc) * 4) = ag[q][v]; } }
	ds_write_b32 v111, v40 offset:16640

; #define LAS __attribute__((address_space(3)))
; __device__ __forceinline__ void rwkv_chunk_group(Frame& F, int bc, unsigned long long& tsub) {
;     ...
;         for (int q = 0; q < 2; ++q) { const int tw = 2 * w + q, m0 = 16 * (tw >> 2), n0 = 16 * (tw & 3);
; #pragma unroll
;             for (int v = 0; v < 4; ++v) { const int t = m0 + 4 * fq + v, cc = n0 + fr;
;                 *(LAS float*)(L + L_WL + (t * 65 + cc) * 4) = aw[q][v]; *(LAS float*)(L + L_AL + (t * 65 + cc) * 4) = aa[q][v]; *(LAS float*)(L + L_GL + (t * 65 + cc) * 4) = ag[q][v]; } }
	ds_write_b32 v111, v44 offset:33280

; #define LAS __attribute__((address_space(3)))
; __device__ __forceinline__ void rwkv_chunk_group(Frame& F, int bc, unsigned long long& tsub) {
;     ...
;         for (int q = 0; q < 2; ++q) { const int tw = 2 * w + q, m0 = 16 * (tw >> 2), n0 = 16 * (tw & 3);
; #pragma unroll
;             for (int v = 0; v < 4; ++v) { const int t = m0 + 4 * fq + v, cc = n0 + fr;
;                 *(LAS float*)(L + L_WL + (t * 65 + cc) * 4) = aw[q][v]; *(LAS float*)(L + L_AL + (t * 65 + cc) * 4) = aa[q][v]; *(LAS float*)(L + L_GL + (t * 65 + cc) * 4) = ag[q][v]; } }
	ds_write_b32 v112, v37

; #define LAS __attribute__((address_space(3)))
; __device__ __forceinline__ void rwkv_chunk_group(Frame& F, int bc, unsigned long long& tsub) {
;     ...
;         for (int q = 0; q < 2; ++q) { const int tw = 2 * w + q, m0 = 16 * (tw >> 2), n0 = 16 * (tw & 3);
; #pragma unroll
;             for (int v = 0; v < 4; ++v) { const int t = m0 + 4 * fq + v, cc = n0 + fr;
;                 *(LAS float*)(L + L_WL + (t * 65 + cc) * 4) = aw[q][v]; *(LAS float*)(L + L_AL + (t * 65 + cc) * 4) = aa[q][v]; *(LAS float*)(L + L_GL + (t * 65 + cc) * 4) = ag[q][v]; } }
	ds_write_b32 v112, v41 offset:16640

; #define LAS __attribute__((address_space(3)))
; __device__ __forceinline__ void rwkv_chunk_group(Frame& F, int bc, unsigned long long& tsub) {
;     ...
;         for (int q = 0; q < 2; ++q) { const int tw = 2 * w + q, m0 = 16 * (tw >> 2), n0 = 16 * (tw & 3);
; #pragma unroll
;             for (int v = 0; v < 4; ++v) { const int t = m0 + 4 * fq + v, cc = n0 + fr;
;                 *(LAS float*)(L + L_WL + (t * 65 + cc) * 4) = aw[q][v]; *(LAS float*)(L + L_AL + (t * 65 + cc) * 4) = aa[q][v]; *(LAS float*)(L + L_GL + (t * 65 + cc) * 4) = ag[q][v]; } }
	ds_write_b32 v112, v45 offset:33280

; #define LAS __attribute__((address_space(3)))
; __device__ __forceinline__ void rwkv_chunk_group(Frame& F, int bc, unsigned long long& tsub) {
;     ...
;         for (int q = 0; q < 2; ++q) { const int tw = 2 * w + q, m0 = 16 * (tw >> 2), n0 = 16 * (tw & 3);
; #pragma unroll
;             for (int v = 0; v < 4; ++v) { const int t = m0 + 4 * fq + v, cc = n0 + fr;
;                 *(LAS float*)(L + L_WL + (t * 65 + cc) * 4) = aw[q][v]; *(LAS float*)(L + L_AL + (t * 65 + cc) * 4) = aa[q][v]; *(LAS float*)(L + L_GL + (t * 65 + cc) * 4) = ag[q][v]; } }
	ds_write_b32 v113, v38

; #define LAS __attribute__((address_space(3)))
; __device__ __forceinline__ void rwkv_chunk_group(Frame& F, int bc, unsigned long long& tsub) {
;     ...
;         for (int q = 0; q < 2; ++q) { const int tw = 2 * w + q, m0 = 16 * (tw >> 2), n0 = 16 * (tw & 3);
; #pragma unroll
;             for (int v = 0; v < 4; ++v) { const int t = m0 + 4 * fq + v, cc = n0 + fr;
;                 *(LAS float*)(L + L_WL + (t * 65 + cc) * 4) = aw[q][v]; *(LAS float*)(L + L_AL + (t * 65 + cc) * 4) = aa[q][v]; *(LAS float*)(L + L_GL + (t * 65 + cc) * 4) = ag[q][v]; } }
	ds_write_b32 v113, v42 offset:16640

; #define LAS __attribute__((address_space(3)))
; __device__ __forceinline__ void rwkv_chunk_group(Frame& F, int bc, unsigned long long& tsub) {
;     ...
;         for (int q = 0; q < 2; ++q) { const int tw = 2 * w + q, m0 = 16 * (tw >> 2), n0 = 16 * (tw & 3);
; #pragma unroll
;             for (int v = 0; v < 4; ++v) { const int t = m0 + 4 * fq + v, cc = n0 + fr;
;                 *(LAS float*)(L + L_WL + (t * 65 + cc) * 4) = aw[q][v]; *(LAS float*)(L + L_AL + (t * 65 + cc) * 4) = aa[q][v]; *(LAS float*)(L + L_GL + (t * 65 + cc) * 4) = ag[q][v]; } }
	ds_write_b32 v113, v46 offset:33280

; #define LAS __attribute__((address_space(3)))
; __device__ __forceinline__ void rwkv_chunk_group(Frame& F, int bc, unsigned long long& tsub) {
;     ...
;         for (int q = 0; q < 2; ++q) { const int tw = 2 * w + q, m0 = 16 * (tw >> 2), n0 = 16 * (tw & 3);
; #pragma unroll
;             for (int v = 0; v < 4; ++v) { const int t = m0 + 4 * fq + v, cc = n0 + fr;
;                 *(LAS float*)(L + L_WL + (t * 65 + cc) * 4) = aw[q][v]; *(LAS float*)(L + L_AL + (t * 65 + cc) * 4) = aa[q][v]; *(LAS float*)(L + L_GL + (t * 65 + cc) * 4) = ag[q][v]; } }
	ds_write_b32 v114, v39

; #define LAS __attribute__((address_space(3)))
; __device__ __forceinline__ void rwkv_chunk_group(Frame& F, int bc, unsigned long long& tsub) {
;     ...
;         for (int q = 0; q < 2; ++q) { const int tw = 2 * w + q, m0 = 16 * (tw >> 2), n0 = 16 * (tw & 3);
; #pragma unroll
;             for (int v = 0; v < 4; ++v) { const int t = m0 + 4 * fq + v, cc = n0 + fr;
;                 *(LAS float*)(L + L_WL + (t * 65 + cc) * 4) = aw[q][v]; *(LAS float*)(L + L_AL + (t * 65 + cc) * 4) = aa[q][v]; *(LAS float*)(L + L_GL + (t * 65 + cc) * 4) = ag[q][v]; } }
	ds_write_b32 v114, v43 offset:16640

; #define LAS __attribute__((address_space(3)))
; __device__ __forceinline__ void rwkv_chunk_group(Frame& F, int bc, unsigned long long& tsub) {
;     ...
;         for (int q = 0; q < 2; ++q) { const int tw = 2 * w + q, m0 = 16 * (tw >> 2), n0 = 16 * (tw & 3);
; #pragma unroll
;             for (int v = 0; v < 4; ++v) { const int t = m0 + 4 * fq + v, cc = n0 + fr;
;                 *(LAS float*)(L + L_WL + (t * 65 + cc) * 4) = aw[q][v]; *(LAS float*)(L + L_AL + (t * 65 + cc) * 4) = aa[q][v]; *(LAS float*)(L + L_GL + (t * 65 + cc) * 4) = ag[q][v]; } }
	ds_write_b32 v114, v47 offset:33280

; #define LAS __attribute__((address_space(3)))
; __device__ __forceinline__ void rwkv_chunk_group(Frame& F, int bc, unsigned long long& tsub) {
;     ...
;         for (int q = 0; q < 2; ++q) { const int tw = 2 * w + q, m0 = 16 * (tw >> 2), n0 = 16 * (tw & 3);
; #pragma unroll
;             for (int v = 0; v < 4; ++v) { const int t = m0 + 4 * fq + v, cc = n0 + fr;
;                 *(LAS float*)(L + L_WL + (t * 65 + cc) * 4) = aw[q][v]; *(LAS float*)(L + L_AL + (t * 65 + cc) * 4) = aa[q][v]; *(LAS float*)(L + L_GL + (t * 65 + cc) * 4) = ag[q][v]; } }
	ds_write_b32 v115, v76

; #define LAS __attribute__((address_space(3)))
; __device__ __forceinline__ void rwkv_chunk_group(Frame& F, int bc, unsigned long long& tsub) {
;     ...
;         for (int q = 0; q < 2; ++q) { const int tw = 2 * w + q, m0 = 16 * (tw >> 2), n0 = 16 * (tw & 3);
; #pragma unroll
;             for (int v = 0; v < 4; ++v) { const int t = m0 + 4 * fq + v, cc = n0 + fr;
;                 *(LAS float*)(L + L_WL + (t * 65 + cc) * 4) = aw[q][v]; *(LAS float*)(L + L_AL + (t * 65 + cc) * 4) = aa[q][v]; *(LAS float*)(L + L_GL + (t * 65 + cc) * 4) = ag[q][v]; } }
	ds_write_b32 v115, v80 offset:16640

; #define LAS __attribute__((address_space(3)))
; __device__ __forceinline__ void rwkv_chunk_group(Frame& F, int bc, unsigned long long& tsub) {
;     ...
;         for (int q = 0; q < 2; ++q) { const int tw = 2 * w + q, m0 = 16 * (tw >> 2), n0 = 16 * (tw & 3);
; #pragma unroll
;             for (int v = 0; v < 4; ++v) { const int t = m0 + 4 * fq + v, cc = n0 + fr;
;                 *(LAS float*)(L + L_WL + (t * 65 + cc) * 4) = aw[q][v]; *(LAS float*)(L + L_AL + (t * 65 + cc) * 4) = aa[q][v]; *(LAS float*)(L + L_GL + (t * 65 + cc) * 4) = ag[q][v]; } }
	ds_write_b32 v115, v84 offset:33280

; #define LAS __attribute__((address_space(3)))
; __device__ __forceinline__ void rwkv_chunk_group(Frame& F, int bc, unsigned long long& tsub) {
;     ...
;         for (int q = 0; q < 2; ++q) { const int tw = 2 * w + q, m0 = 16 * (tw >> 2), n0 = 16 * (tw & 3);
; #pragma unroll
;             for (int v = 0; v < 4; ++v) { const int t = m0 + 4 * fq + v, cc = n0 + fr;
;                 *(LAS float*)(L + L_WL + (t * 65 + cc) * 4) = aw[q][v]; *(LAS float*)(L + L_AL + (t * 65 + cc) * 4) = aa[q][v]; *(LAS float*)(L + L_GL + (t * 65 + cc) * 4) = ag[q][v]; } }
	ds_write_b32 v116, v77

; #define LAS __attribute__((address_space(3)))
; __device__ __forceinline__ void rwkv_chunk_group(Frame& F, int bc, unsigned long long& tsub) {
;     ...
;         for (int q = 0; q < 2; ++q) { const int tw = 2 * w + q, m0 = 16 * (tw >> 2), n0 = 16 * (tw & 3);
; #pragma unroll
;             for (int v = 0; v < 4; ++v) { const int t = m0 + 4 * fq + v, cc = n0 + fr;
;                 *(LAS float*)(L + L_WL + (t * 65 + cc) * 4) = aw[q][v]; *(LAS float*)(L + L_AL + (t * 65 + cc) * 4) = aa[q][v]; *(LAS float*)(L + L_GL + (t * 65 + cc) * 4) = ag[q][v]; } }
	ds_write_b32 v116, v81 offset:16640

; #define LAS __attribute__((address_space(3)))
; __device__ __forceinline__ void rwkv_chunk_group(Frame& F, int bc, unsigned long long& tsub) {
;     ...
;         for (int q = 0; q < 2; ++q) { const int tw = 2 * w + q, m0 = 16 * (tw >> 2), n0 = 16 * (tw & 3);
; #pragma unroll
;             for (int v = 0; v < 4; ++v) { const int t = m0 + 4 * fq + v, cc = n0 + fr;
;                 *(LAS float*)(L + L_WL + (t * 65 + cc) * 4) = aw[q][v]; *(LAS float*)(L + L_AL + (t * 65 + cc) * 4) = aa[q][v]; *(LAS float*)(L + L_GL + (t * 65 + cc) * 4) = ag[q][v]; } }
	ds_write_b32 v116, v85 offset:33280

; #define LAS __attribute__((address_space(3)))
; __device__ __forceinline__ void rwkv_chunk_group(Frame& F, int bc, unsigned long long& tsub) {
;     ...
;         for (int q = 0; q < 2; ++q) { const int tw = 2 * w + q, m0 = 16 * (tw >> 2), n0 = 16 * (tw & 3);
; #pragma unroll
;             for (int v = 0; v < 4; ++v) { const int t = m0 + 4 * fq + v, cc = n0 + fr;
;                 *(LAS float*)(L + L_WL + (t * 65 + cc) * 4) = aw[q][v]; *(LAS float*)(L + L_AL + (t * 65 + cc) * 4) = aa[q][v]; *(LAS float*)(L + L_GL + (t * 65 + cc) * 4) = ag[q][v]; } }
	ds_write_b32 v117, v78

; #define LAS __attribute__((address_space(3)))
; __device__ __forceinline__ void rwkv_chunk_group(Frame& F, int bc, unsigned long long& tsub) {
;     ...
;         for (int q = 0; q < 2; ++q) { const int tw = 2 * w + q, m0 = 16 * (tw >> 2), n0 = 16 * (tw & 3);
; #pragma unroll
;             for (int v = 0; v < 4; ++v) { const int t = m0 + 4 * fq + v, cc = n0 + fr;
;                 *(LAS float*)(L + L_WL + (t * 65 + cc) * 4) = aw[q][v]; *(LAS float*)(L + L_AL + (t * 65 + cc) * 4) = aa[q][v]; *(LAS float*)(L + L_GL + (t * 65 + cc) * 4) = ag[q][v]; } }
	ds_write_b32 v117, v82 offset:16640

; #define LAS __attribute__((address_space(3)))
; __device__ __forceinline__ void rwkv_chunk_group(Frame& F, int bc, unsigned long long& tsub) {
;     ...
;         for (int q = 0; q < 2; ++q) { const int tw = 2 * w + q, m0 = 16 * (tw >> 2), n0 = 16 * (tw & 3);
; #pragma unroll
;             for (int v = 0; v < 4; ++v) { const int t = m0 + 4 * fq + v, cc = n0 + fr;
;                 *(LAS float*)(L + L_WL + (t * 65 + cc) * 4) = aw[q][v]; *(LAS float*)(L + L_AL + (t * 65 + cc) * 4) = aa[q][v]; *(LAS float*)(L + L_GL + (t * 65 + cc) * 4) = ag[q][v]; } }
	ds_write_b32 v117, v86 offset:33280

; #define LAS __attribute__((address_space(3)))
; __device__ __forceinline__ void rwkv_chunk_group(Frame& F, int bc, unsigned long long& tsub) {
;     ...
;         for (int q = 0; q < 2; ++q) { const int tw = 2 * w + q, m0 = 16 * (tw >> 2), n0 = 16 * (tw & 3);
; #pragma unroll
;             for (int v = 0; v < 4; ++v) { const int t = m0 + 4 * fq + v, cc = n0 + fr;
;                 *(LAS float*)(L + L_WL + (t * 65 + cc) * 4) = aw[q][v]; *(LAS float*)(L + L_AL + (t * 65 + cc) * 4) = aa[q][v]; *(LAS float*)(L + L_GL + (t * 65 + cc) * 4) = ag[q][v]; } }
	ds_write_b32 v118, v79

; #define LAS __attribute__((address_space(3)))
; __device__ __forceinline__ void rwkv_chunk_group(Frame& F, int bc, unsigned long long& tsub) {
;     ...
;         for (int q = 0; q < 2; ++q) { const int tw = 2 * w + q, m0 = 16 * (tw >> 2), n0 = 16 * (tw & 3);
; #pragma unroll
;             for (int v = 0; v < 4; ++v) { const int t = m0 + 4 * fq + v, cc = n0 + fr;
;                 *(LAS float*)(L + L_WL + (t * 65 + cc) * 4) = aw[q][v]; *(LAS float*)(L + L_AL + (t * 65 + cc) * 4) = aa[q][v]; *(LAS float*)(L + L_GL + (t * 65 + cc) * 4) = ag[q][v]; } }
	ds_write_b32 v118, v83 offset:16640

; #define LAS __attribute__((address_space(3)))
; __device__ __forceinline__ void rwkv_chunk_group(Frame& F, int bc, unsigned long long& tsub) {
;     ...
;         for (int q = 0; q < 2; ++q) { const int tw = 2 * w + q, m0 = 16 * (tw >> 2), n0 = 16 * (tw & 3);
; #pragma unroll
;             for (int v = 0; v < 4; ++v) { const int t = m0 + 4 * fq + v, cc = n0 + fr;
;                 *(LAS float*)(L + L_WL + (t * 65 + cc) * 4) = aw[q][v]; *(LAS float*)(L + L_AL + (t * 65 + cc) * 4) = aa[q][v]; *(LAS float*)(L + L_GL + (t * 65 + cc) * 4) = ag[q][v]; } }
	ds_write_b32 v118, v87 offset:33280


; #define LAS __attribute__((address_space(3)))
; #define LBAR() asm volatile("s_waitcnt lgkmcnt(0)\n\ts_barrier" ::: "memory")
; __device__ __forceinline__ void rwkv_chunk_group(Frame& F, int bc, unsigned long long& tsub) {
;     ...
;         LBAR();
;     ...
;             const float wl = *(const LAS float*)(L + L_WL + (t * 65 + ch) * 4), al = *(const LAS float*)(L + L_AL + (t * 65 + ch) * 4), gl = *(const LAS float*)(L + L_GL + (t * 65 + ch) * 4);
	s_waitcnt lgkmcnt(0)
	s_barrier


; __device__ __forceinline__ void rwkv_chunk_group(Frame& F, int bc, unsigned long long& tsub) {
;     ...
;         const float mur = mu[gc], muk = mu[512 + gc], muv = mu[1024 + gc];
;         const float w0 = (PRM + 2048)[gc], a0 = (PRM + 2560)[gc], k_k = (PRM + 3072)[gc], k_a = (PRM + 3584)[gc], r_k = (PRM + 4096)[gc];
;         float rr[8], kp[8], vv[8], aa[8], bb[8], ld[8], vbv[8], ggv[8];
;         float pr = bf2f(raw[0][0]), pk = bf2f(raw[0][1]), pv = bf2f(raw[0][2]);
;         bf16* VBp = (bf16*)(F.ws + WS_VB) + (size_t)item * 4096; bf16* Gp = (bf16*)(F.ws + WS_G) + (size_t)item * 4096;
;         float run = 0.f; float kkv[8], icv[8], sq[8], bq[8];
; #pragma unroll
;         for (int tt = 0; tt < 8; ++tt) { const int t = tb + tt;
;             const float cr = bf2f(raw[tt + 1][0]), ck = bf2f(raw[tt + 1][1]), cv = bf2f(raw[tt + 1][2]);
;             const float r = cr + (pr - cr) * mur, k = ck + (pk - ck) * muk, v = cv + (pv - cv) * muv; pr = cr; pk = ck; pv = cv;
	s_waitcnt vmcnt(0)
	v_mov_b32_e32 v95, v224
	v_mov_b32_e32 v42, v225


; __device__ __forceinline__ void rwkv_chunk_group(Frame& F, int bc, unsigned long long& tsub) {
;     ...
;         for (int tt = 0; tt < 8; ++tt) { const int t = tb + tt;
;             const float cr = bf2f(raw[tt + 1][0]), ck = bf2f(raw[tt + 1][1]), cv = bf2f(raw[tt + 1][2]);
;             const float r = cr + (pr - cr) * mur, k = ck + (pk - ck) * muk, v = cv + (pv - cv) * muv; pr = cr; pk = ck; pv = cv;
	s_nop 0


; #define LAS __attribute__((address_space(3)))
; __device__ __forceinline__ void rwkv_chunk_group(Frame& F, int bc, unsigned long long& tsub) {
;     ...
;         const float mur = mu[gc], muk = mu[512 + gc], muv = mu[1024 + gc];
;         const float w0 = (PRM + 2048)[gc], a0 = (PRM + 2560)[gc], k_k = (PRM + 3072)[gc], k_a = (PRM + 3584)[gc], r_k = (PRM + 4096)[gc];
;         float rr[8], kp[8], vv[8], aa[8], bb[8], ld[8], vbv[8], ggv[8];
;         float pr = bf2f(raw[0][0]), pk = bf2f(raw[0][1]), pv = bf2f(raw[0][2]);
;         bf16* VBp = (bf16*)(F.ws + WS_VB) + (size_t)item * 4096; bf16* Gp = (bf16*)(F.ws + WS_G) + (size_t)item * 4096;
;         float run = 0.f; float kkv[8], icv[8], sq[8], bq[8];
; #pragma unroll
;         for (int tt = 0; tt < 8; ++tt) { const int t = tb + tt;
;             const float cr = bf2f(raw[tt + 1][0]), ck = bf2f(raw[tt + 1][1]), cv = bf2f(raw[tt + 1][2]);
;             const float r = cr + (pr - cr) * mur, k = ck + (pk - ck) * muk, v = cv + (pv - cv) * muv; pr = cr; pk = ck; pv = cv;
;             const float wl = *(const LAS float*)(L + L_WL + (t * 65 + ch) * 4), al = *(const LAS float*)(L + L_AL + (t * 65 + ch) * 4), gl = *(const LAS float*)(L + L_GL + (t * 65 + ch) * 4);
	v_mov_b32_e32 v52, v226


; __device__ __forceinline__ void rwkv_chunk_group(Frame& F, int bc, unsigned long long& tsub) {
;     ...
;         const float mur = mu[gc], muk = mu[512 + gc], muv = mu[1024 + gc];
;         const float w0 = (PRM + 2048)[gc], a0 = (PRM + 2560)[gc], k_k = (PRM + 3072)[gc], k_a = (PRM + 3584)[gc], r_k = (PRM + 4096)[gc];
	v_mov_b32_e32 v45, v227


; __device__ __forceinline__ void rwkv_chunk_group(Frame& F, int bc, unsigned long long& tsub) {
;     ...
;             const float cr = bf2f(raw[tt + 1][0]), ck = bf2f(raw[tt + 1][1]), cv = bf2f(raw[tt + 1][2]);
	v_lshlrev_b32_e32 v82, 16, v155
	v_and_b32_e32 v77, 0xffff0000, v167

; __device__ __forceinline__ void rwkv_chunk_group(Frame& F, int bc, unsigned long long& tsub) {
;     ...
;         const float mur = mu[gc], muk = mu[512 + gc], muv = mu[1024 + gc];
;         const float w0 = (PRM + 2048)[gc], a0 = (PRM + 2560)[gc], k_k = (PRM + 3072)[gc], k_a = (PRM + 3584)[gc], r_k = (PRM + 4096)[gc];
	v_mov_b32_e32 v43, v228


; __device__ __forceinline__ void rwkv_chunk_group(Frame& F, int bc, unsigned long long& tsub) {
;     ...
;             const float cr = bf2f(raw[tt + 1][0]), ck = bf2f(raw[tt + 1][1]), cv = bf2f(raw[tt + 1][2]);
	v_lshlrev_b32_e32 v76, 16, v167
	v_and_b32_e32 v79, 0xffff0000, v166


; __device__ __forceinline__ void rwkv_chunk_group(Frame& F, int bc, unsigned long long& tsub) {
;     ...
;         const float mur = mu[gc], muk = mu[512 + gc], muv = mu[1024 + gc];
;         const float w0 = (PRM + 2048)[gc], a0 = (PRM + 2560)[gc], k_k = (PRM + 3072)[gc], k_a = (PRM + 3584)[gc], r_k = (PRM + 4096)[gc];
;         float rr[8], kp[8], vv[8], aa[8], bb[8], ld[8], vbv[8], ggv[8];
;         float pr = bf2f(raw[0][0]), pk = bf2f(raw[0][1]), pv = bf2f(raw[0][2]);
;         bf16* VBp = (bf16*)(F.ws + WS_VB) + (size_t)item * 4096; bf16* Gp = (bf16*)(F.ws + WS_G) + (size_t)item * 4096;
;         float run = 0.f; float kkv[8], icv[8], sq[8], bq[8];
; #pragma unroll
;         for (int tt = 0; tt < 8; ++tt) { const int t = tb + tt;
;             const float cr = bf2f(raw[tt + 1][0]), ck = bf2f(raw[tt + 1][1]), cv = bf2f(raw[tt + 1][2]);
	v_mov_b32_e32 v44, v229
	v_lshlrev_b32_e32 v78, 16, v166

; __device__ __forceinline__ void rwkv_chunk_group(Frame& F, int bc, unsigned long long& tsub) {
;     ...
;         const float mur = mu[gc], muk = mu[512 + gc], muv = mu[1024 + gc];
;         const float w0 = (PRM + 2048)[gc], a0 = (PRM + 2560)[gc], k_k = (PRM + 3072)[gc], k_a = (PRM + 3584)[gc], r_k = (PRM + 4096)[gc];
	v_mov_b32_e32 v46, v230


; __device__ __forceinline__ void rwkv_chunk_group(Frame& F, int bc, unsigned long long& tsub) {
;     ...
;             const float cr = bf2f(raw[tt + 1][0]), ck = bf2f(raw[tt + 1][1]), cv = bf2f(raw[tt + 1][2]);
	v_lshlrev_b32_e32 v86, 16, v157
	v_and_b32_e32 v91, 0xffff0000, v168

; #define LAS __attribute__((address_space(3)))
; __device__ __forceinline__ void rwkv_chunk_group(Frame& F, int bc, unsigned long long& tsub) {
;     ...
;             const float cr = bf2f(raw[tt + 1][0]), ck = bf2f(raw[tt + 1][1]), cv = bf2f(raw[tt + 1][2]);
;             const float r = cr + (pr - cr) * mur, k = ck + (pk - ck) * muk, v = cv + (pv - cv) * muv; pr = cr; pk = ck; pv = cv;
;             const float wl = *(const LAS float*)(L + L_WL + (t * 65 + ch) * 4), al = *(const LAS float*)(L + L_AL + (t * 65 + ch) * 4), gl = *(const LAS float*)(L + L_GL + (t * 65 + ch) * 4);
	v_mov_b32_e32 v103, v231
	v_lshlrev_b32_e32 v36, 16, v153
	v_lshlrev_b32_e32 v37, 16, v154
	v_sub_f32_e32 v36, v36, v37


; #define LAS __attribute__((address_space(3)))
; __device__ __forceinline__ void rwkv_chunk_group(Frame& F, int bc, unsigned long long& tsub) {
;     ...
;             const float r = cr + (pr - cr) * mur, k = ck + (pk - ck) * muk, v = cv + (pv - cv) * muv; pr = cr; pk = ck; pv = cv;
;             const float wl = *(const LAS float*)(L + L_WL + (t * 65 + ch) * 4), al = *(const LAS float*)(L + L_AL + (t * 65 + ch) * 4), gl = *(const LAS float*)(L + L_GL + (t * 65 + ch) * 4);
	ds_read_b32 v38, v119 offset:16640
	ds_read_b32 v47, v119 offset:33280
	ds_read_b32 v177, v120 offset:33280
	ds_read_b32 v185, v122 offset:33280
	ds_read_b32 v191, v125 offset:16640
	v_lshlrev_b32_e32 v90, 16, v168
	v_and_b32_e32 v85, 0xffff0000, v169
	ds_read_b32 v182, v121 offset:33280
	ds_read_b32 v96, v124 offset:16640
	ds_read_b32 v189, v123 offset:33280
	ds_read_b32 v193, v124 offset:33280
	ds_read_b32 v194, v125 offset:33280
	s_waitcnt vmcnt(7)
	v_fma_f32 v173, v36, v95, v37

; __device__ __forceinline__ void rwkv_chunk_group(Frame& F, int bc, unsigned long long& tsub) {
;     ...
;             const float z = -(w0 + wl); const float sp = fmaxf(z, 0.f) + __logf(1.f + __expf(-fabsf(z)));
	ds_read_b32 v36, v119
	s_waitcnt vmcnt(4) lgkmcnt(0)
	v_add_f32_e32 v36, v45, v36
	v_max_f32_e64 v39, -v36, 0
	v_mul_f32_e64 v36, |v36|, s1
	v_exp_f32_e32 v36, v36
	s_nop 0
	v_add_f32_e32 v36, 1.0, v36

; __device__ __forceinline__ void rwkv_chunk_group(Frame& F, int bc, unsigned long long& tsub) {
;     ...
;             const float z = -(w0 + wl); const float sp = fmaxf(z, 0.f) + __logf(1.f + __expf(-fabsf(z)));
	s_nop 1


; __device__ __forceinline__ void rwkv_chunk_group(Frame& F, int bc, unsigned long long& tsub) {
;     ...
;             const float z = -(w0 + wl); const float sp = fmaxf(z, 0.f) + __logf(1.f + __expf(-fabsf(z)));
	v_log_f32_e32 v36, v36
	s_nop 0
	v_mul_f32_e32 v40, 0x3f317217, v36
	v_fma_f32 v40, v36, s9, -v40
	v_fmac_f32_e32 v40, 0x3377d1cf, v36
	v_fmac_f32_e32 v40, 0x3f317217, v36

; __device__ __forceinline__ void rwkv_chunk_group(Frame& F, int bc, unsigned long long& tsub) {
;     ...
;             const float z = -(w0 + wl); const float sp = fmaxf(z, 0.f) + __logf(1.f + __expf(-fabsf(z)));
	s_nop 1
	v_mov_b32_e32 v36, v40


; __device__ __forceinline__ void rwkv_chunk_group(Frame& F, int bc, unsigned long long& tsub) {
;     ...
;             const float z = -(w0 + wl); const float sp = fmaxf(z, 0.f) + __logf(1.f + __expf(-fabsf(z)));
	v_add_f32_e32 v36, v39, v36

; __device__ __forceinline__ float sigmoidf_(float x) { return __builtin_amdgcn_rcpf(1.0f + __expf(-x)); }
; __device__ __forceinline__ void rwkv_chunk_group(Frame& F, int bc, unsigned long long& tsub) {
;     ...
;             const float lgd = -__expf(-sp - 0.5f);
;             const float ic = sigmoidf_(a0 + al);
	ds_read_b32 v39, v120
	v_sub_f32_e32 v36, -0.5, v36
	v_mul_f32_e32 v36, 0x3fb8aa3b, v36
	v_exp_f32_e32 v102, v36
	s_waitcnt vmcnt(3)
	v_add_f32_e32 v36, v43, v38
	v_mul_f32_e32 v36, 0xbfb8aa3b, v36

; #define LAS __attribute__((address_space(3)))
; __device__ __forceinline__ float sigmoidf_(float x) { return __builtin_amdgcn_rcpf(1.0f + __expf(-x)); }
; __device__ __forceinline__ void rwkv_chunk_group(Frame& F, int bc, unsigned long long& tsub) {
;     ...
;             const float r = cr + (pr - cr) * mur, k = ck + (pk - ck) * muk, v = cv + (pv - cv) * muv; pr = cr; pk = ck; pv = cv;
;             const float wl = *(const LAS float*)(L + L_WL + (t * 65 + ch) * 4), al = *(const LAS float*)(L + L_AL + (t * 65 + ch) * 4), gl = *(const LAS float*)(L + L_GL + (t * 65 + ch) * 4);
;             const float z = -(w0 + wl); const float sp = fmaxf(z, 0.f) + __logf(1.f + __expf(-fabsf(z)));
;             const float lgd = -__expf(-sp - 0.5f);
;             const float ic = sigmoidf_(a0 + al);
	v_exp_f32_e32 v36, v36
	ds_read_b32 v40, v120 offset:16640
	s_waitcnt lgkmcnt(1)
	v_add_f32_e32 v39, v45, v39
	v_max_f32_e64 v41, -v39, 0
	v_mul_f32_e64 v39, |v39|, s1
	v_exp_f32_e32 v39, v39
	v_add_f32_e32 v36, 1.0, v36
	v_rcp_f32_e32 v38, v36
	v_sub_f32_e32 v36, v37, v82
	v_fma_f32 v174, v36, v95, v82
	v_and_b32_e32 v37, 0xffff0000, v161
	v_lshlrev_b32_e32 v36, 16, v161
	v_add_f32_e32 v39, 1.0, v39
	v_pk_add_f32 v[36:37], v[36:37], v[76:77] neg_lo:[0,1] neg_hi:[0,1]

; __device__ __forceinline__ void rwkv_chunk_group(Frame& F, int bc, unsigned long long& tsub) {
;     ...
;             const float r = cr + (pr - cr) * mur, k = ck + (pk - ck) * muk, v = cv + (pv - cv) * muv; pr = cr; pk = ck; pv = cv;
	v_pk_fma_f32 v[36:37], v[36:37], v[52:53], v[76:77] op_sel_hi:[1,0,1]
	s_nop 0


; __device__ __forceinline__ void rwkv_chunk_group(Frame& F, int bc, unsigned long long& tsub) {
;     ...
;             const float z = -(w0 + wl); const float sp = fmaxf(z, 0.f) + __logf(1.f + __expf(-fabsf(z)));
	v_log_f32_e32 v39, v39
	s_nop 0
	v_mul_f32_e32 v76, 0x3f317217, v39
	v_fma_f32 v76, v39, s9, -v76
	v_fmac_f32_e32 v76, 0x3377d1cf, v39
	v_fmac_f32_e32 v76, 0x3f317217, v39

; __device__ __forceinline__ void rwkv_chunk_group(Frame& F, int bc, unsigned long long& tsub) {
;     ...
;             const float z = -(w0 + wl); const float sp = fmaxf(z, 0.f) + __logf(1.f + __expf(-fabsf(z)));
	s_nop 1
	v_mov_b32_e32 v39, v76


; #define LAS __attribute__((address_space(3)))
; __device__ __forceinline__ float sigmoidf_(float x) { return __builtin_amdgcn_rcpf(1.0f + __expf(-x)); }
; __device__ __forceinline__ void rwkv_chunk_group(Frame& F, int bc, unsigned long long& tsub) {
;     ...
;             const float r = cr + (pr - cr) * mur, k = ck + (pk - ck) * muk, v = cv + (pv - cv) * muv; pr = cr; pk = ck; pv = cv;
;             const float wl = *(const LAS float*)(L + L_WL + (t * 65 + ch) * 4), al = *(const LAS float*)(L + L_AL + (t * 65 + ch) * 4), gl = *(const LAS float*)(L + L_GL + (t * 65 + ch) * 4);
;             const float z = -(w0 + wl); const float sp = fmaxf(z, 0.f) + __logf(1.f + __expf(-fabsf(z)));
;             const float lgd = -__expf(-sp - 0.5f);
;             const float ic = sigmoidf_(a0 + al);
;             const float kv = k * k_k; const float kq = k * (1.f + (ic - 1.f) * k_a);
;             kkv[tt] = kv; icv[tt] = ic; sq[tt] = kv * kv; bq[tt] = r * kq * r_k;
;             rr[tt] = r; kp[tt] = kq; vv[tt] = v; run += lgd; ld[tt] = run; ggv[tt] = gl;
	v_add_f32_e32 v39, v41, v39
	v_sub_f32_e32 v39, -0.5, v39
	v_mul_f32_e32 v39, 0x3fb8aa3b, v39
	v_exp_f32_e32 v76, v39
	s_waitcnt lgkmcnt(0)
	v_add_f32_e32 v39, v43, v40
	v_mul_f32_e32 v39, 0xbfb8aa3b, v39
	v_exp_f32_e32 v39, v39
	v_and_b32_e32 v41, 0xffff0000, v160
	v_lshlrev_b32_e32 v40, 16, v160
	v_pk_add_f32 v[40:41], v[40:41], v[78:79] neg_lo:[0,1] neg_hi:[0,1]
	v_add_f32_e32 v39, 1.0, v39
	v_rcp_f32_e32 v39, v39
	v_pk_fma_f32 v[80:81], v[40:41], v[42:43], v[78:79] op_sel_hi:[1,0,1]
	v_sub_f32_e64 v176, -v102, v76
	v_lshlrev_b32_e32 v76, 16, v156
	v_pk_add_f32 v[40:41], v[38:39], -1.0 op_sel_hi:[1,0]
	s_waitcnt vmcnt(1)
	v_pk_fma_f32 v[40:41], v[46:47], v[40:41], 1.0 op_sel_hi:[0,1,0]
	v_pk_mul_f32 v[40:41], v[80:81], v[40:41]
	s_nop 0
	v_mul_f32_e32 v78, v173, v40
	s_waitcnt vmcnt(0)
	v_mul_f32_e32 v101, v103, v78
	v_mul_f32_e32 v78, v174, v41
	v_mul_f32_e32 v100, v103, v78
	v_sub_f32_e32 v78, v82, v76
	v_fma_f32 v175, v78, v95, v76

; #define LAS __attribute__((address_space(3)))
; __device__ __forceinline__ void rwkv_chunk_group(Frame& F, int bc, unsigned long long& tsub) {
;     ...
;             const float wl = *(const LAS float*)(L + L_WL + (t * 65 + ch) * 4), al = *(const LAS float*)(L + L_AL + (t * 65 + ch) * 4), gl = *(const LAS float*)(L + L_GL + (t * 65 + ch) * 4);
	ds_read_b32 v78, v121

; #define LAS __attribute__((address_space(3)))
; __device__ __forceinline__ float sigmoidf_(float x) { return __builtin_amdgcn_rcpf(1.0f + __expf(-x)); }
; __device__ __forceinline__ void rwkv_chunk_group(Frame& F, int bc, unsigned long long& tsub) {
;     ...
;             const float r = cr + (pr - cr) * mur, k = ck + (pk - ck) * muk, v = cv + (pv - cv) * muv; pr = cr; pk = ck; pv = cv;
;             const float wl = *(const LAS float*)(L + L_WL + (t * 65 + ch) * 4), al = *(const LAS float*)(L + L_AL + (t * 65 + ch) * 4), gl = *(const LAS float*)(L + L_GL + (t * 65 + ch) * 4);
;             const float z = -(w0 + wl); const float sp = fmaxf(z, 0.f) + __logf(1.f + __expf(-fabsf(z)));
;             const float lgd = -__expf(-sp - 0.5f);
;             const float ic = sigmoidf_(a0 + al);
	ds_read_b32 v82, v121 offset:16640
	v_sub_f32_e32 v76, v76, v86
	v_fma_f32 v178, v76, v95, v86
	s_waitcnt lgkmcnt(1)
	v_add_f32_e32 v78, v45, v78
	v_max_f32_e64 v83, -v78, 0
	v_mul_f32_e64 v78, |v78|, s1
	v_exp_f32_e32 v78, v78
	s_waitcnt lgkmcnt(0)
	v_add_f32_e32 v82, v43, v82
	v_mul_f32_e32 v82, 0xbfb8aa3b, v82
	v_exp_f32_e32 v82, v82
	v_add_f32_e32 v78, 1.0, v78

; __device__ __forceinline__ float sigmoidf_(float x) { return __builtin_amdgcn_rcpf(1.0f + __expf(-x)); }
; __device__ __forceinline__ void rwkv_chunk_group(Frame& F, int bc, unsigned long long& tsub) {
;     ...
;             const float z = -(w0 + wl); const float sp = fmaxf(z, 0.f) + __logf(1.f + __expf(-fabsf(z)));
;             const float lgd = -__expf(-sp - 0.5f);
;             const float ic = sigmoidf_(a0 + al);
	v_add_f32_e32 v82, 1.0, v82
	s_nop 0


; __device__ __forceinline__ float sigmoidf_(float x) { return __builtin_amdgcn_rcpf(1.0f + __expf(-x)); }
; __device__ __forceinline__ void rwkv_chunk_group(Frame& F, int bc, unsigned long long& tsub) {
;     ...
;             const float z = -(w0 + wl); const float sp = fmaxf(z, 0.f) + __logf(1.f + __expf(-fabsf(z)));
;             const float lgd = -__expf(-sp - 0.5f);
;             const float ic = sigmoidf_(a0 + al);
	v_log_f32_e32 v78, v78
	v_rcp_f32_e32 v82, v82
	v_mul_f32_e32 v84, 0x3f317217, v78
	v_fma_f32 v84, v78, s9, -v84
	v_fmac_f32_e32 v84, 0x3377d1cf, v78
	v_fmac_f32_e32 v84, 0x3f317217, v78

; __device__ __forceinline__ void rwkv_chunk_group(Frame& F, int bc, unsigned long long& tsub) {
;     ...
;             const float z = -(w0 + wl); const float sp = fmaxf(z, 0.f) + __logf(1.f + __expf(-fabsf(z)));
	s_nop 1
	v_mov_b32_e32 v78, v84


; __device__ __forceinline__ void rwkv_chunk_group(Frame& F, int bc, unsigned long long& tsub) {
;     ...
;             const float z = -(w0 + wl); const float sp = fmaxf(z, 0.f) + __logf(1.f + __expf(-fabsf(z)));
;             const float lgd = -__expf(-sp - 0.5f);
	v_add_f32_e32 v78, v83, v78
	v_sub_f32_e32 v78, -0.5, v78
	v_mul_f32_e32 v78, 0x3fb8aa3b, v78
	v_exp_f32_e32 v78, v78

; #define LAS __attribute__((address_space(3)))
; __device__ __forceinline__ float sigmoidf_(float x) { return __builtin_amdgcn_rcpf(1.0f + __expf(-x)); }
; __device__ __forceinline__ void rwkv_chunk_group(Frame& F, int bc, unsigned long long& tsub) {
;     ...
;             const float wl = *(const LAS float*)(L + L_WL + (t * 65 + ch) * 4), al = *(const LAS float*)(L + L_AL + (t * 65 + ch) * 4), gl = *(const LAS float*)(L + L_GL + (t * 65 + ch) * 4);
;             const float z = -(w0 + wl); const float sp = fmaxf(z, 0.f) + __logf(1.f + __expf(-fabsf(z)));
;             const float lgd = -__expf(-sp - 0.5f);
;             const float ic = sigmoidf_(a0 + al);
;             const float kv = k * k_k; const float kq = k * (1.f + (ic - 1.f) * k_a);
;             kkv[tt] = kv; icv[tt] = ic; sq[tt] = kv * kv; bq[tt] = r * kq * r_k;
;             rr[tt] = r; kp[tt] = kq; vv[tt] = v; run += lgd; ld[tt] = run; ggv[tt] = gl;
	ds_read_b32 v83, v122 offset:16640
	v_lshlrev_b32_e32 v84, 16, v169
	v_sub_f32_e32 v179, v176, v78

; #define LAS __attribute__((address_space(3)))
; __device__ __forceinline__ void rwkv_chunk_group(Frame& F, int bc, unsigned long long& tsub) {
;     ...
;             const float r = cr + (pr - cr) * mur, k = ck + (pk - ck) * muk, v = cv + (pv - cv) * muv; pr = cr; pk = ck; pv = cv;
;             const float wl = *(const LAS float*)(L + L_WL + (t * 65 + ch) * 4), al = *(const LAS float*)(L + L_AL + (t * 65 + ch) * 4), gl = *(const LAS float*)(L + L_GL + (t * 65 + ch) * 4);
;             const float z = -(w0 + wl); const float sp = fmaxf(z, 0.f) + __logf(1.f + __expf(-fabsf(z)));
	ds_read_b32 v78, v122
	v_pk_mov_b32 v[76:77], v[76:77], v[84:85] op_sel:[1,0]
	s_waitcnt lgkmcnt(0)
	v_add_f32_e32 v78, v45, v78
	v_max_f32_e64 v87, -v78, 0
	v_mul_f32_e64 v78, |v78|, s1
	v_exp_f32_e32 v78, v78
	v_pk_add_f32 v[76:77], v[76:77], v[84:85] neg_lo:[0,1] neg_hi:[0,1]
	v_add_f32_e32 v78, 1.0, v78

; __device__ __forceinline__ void rwkv_chunk_group(Frame& F, int bc, unsigned long long& tsub) {
;     ...
;             const float r = cr + (pr - cr) * mur, k = ck + (pk - ck) * muk, v = cv + (pv - cv) * muv; pr = cr; pk = ck; pv = cv;
	v_pk_fma_f32 v[76:77], v[76:77], v[52:53], v[84:85] op_sel_hi:[1,0,1]
	s_nop 0


; __device__ __forceinline__ void rwkv_chunk_group(Frame& F, int bc, unsigned long long& tsub) {
;     ...
;             const float z = -(w0 + wl); const float sp = fmaxf(z, 0.f) + __logf(1.f + __expf(-fabsf(z)));
	v_log_f32_e32 v78, v78
	s_nop 0
	v_mul_f32_e32 v88, 0x3f317217, v78
	v_fma_f32 v88, v78, s9, -v88
	v_fmac_f32_e32 v88, 0x3377d1cf, v78
	v_fmac_f32_e32 v88, 0x3f317217, v78

; __device__ __forceinline__ void rwkv_chunk_group(Frame& F, int bc, unsigned long long& tsub) {
;     ...
;             const float z = -(w0 + wl); const float sp = fmaxf(z, 0.f) + __logf(1.f + __expf(-fabsf(z)));
	s_nop 1
	v_mov_b32_e32 v78, v88


; #define LAS __attribute__((address_space(3)))
; __device__ __forceinline__ float sigmoidf_(float x) { return __builtin_amdgcn_rcpf(1.0f + __expf(-x)); }
; __device__ __forceinline__ void rwkv_chunk_group(Frame& F, int bc, unsigned long long& tsub) {
;     ...
;             const float r = cr + (pr - cr) * mur, k = ck + (pk - ck) * muk, v = cv + (pv - cv) * muv; pr = cr; pk = ck; pv = cv;
;             const float wl = *(const LAS float*)(L + L_WL + (t * 65 + ch) * 4), al = *(const LAS float*)(L + L_AL + (t * 65 + ch) * 4), gl = *(const LAS float*)(L + L_GL + (t * 65 + ch) * 4);
;             const float z = -(w0 + wl); const float sp = fmaxf(z, 0.f) + __logf(1.f + __expf(-fabsf(z)));
;             const float lgd = -__expf(-sp - 0.5f);
;             const float ic = sigmoidf_(a0 + al);
;             const float kv = k * k_k; const float kq = k * (1.f + (ic - 1.f) * k_a);
;             kkv[tt] = kv; icv[tt] = ic; sq[tt] = kv * kv; bq[tt] = r * kq * r_k;
;             rr[tt] = r; kp[tt] = kq; vv[tt] = v; run += lgd; ld[tt] = run; ggv[tt] = gl;
	v_add_f32_e32 v78, v87, v78
	v_sub_f32_e32 v78, -0.5, v78
	v_mul_f32_e32 v78, 0x3fb8aa3b, v78
	v_exp_f32_e32 v87, v78
	v_add_f32_e32 v78, v43, v83
	v_mul_f32_e32 v78, 0xbfb8aa3b, v78
	v_exp_f32_e32 v78, v78
	v_sub_f32_e32 v181, v179, v87
	v_lshlrev_b32_e32 v87, 16, v158
	v_sub_f32_e32 v86, v86, v87
	v_add_f32_e32 v78, 1.0, v78
	v_rcp_f32_e32 v83, v78
	v_pk_mov_b32 v[78:79], v[78:79], v[90:91] op_sel:[1,0]
	v_fma_f32 v180, v86, v95, v87
	v_pk_add_f32 v[78:79], v[78:79], v[90:91] neg_lo:[0,1] neg_hi:[0,1]

; #define LAS __attribute__((address_space(3)))
; __device__ __forceinline__ float sigmoidf_(float x) { return __builtin_amdgcn_rcpf(1.0f + __expf(-x)); }
; __device__ __forceinline__ void rwkv_chunk_group(Frame& F, int bc, unsigned long long& tsub) {
;     ...
;             const float r = cr + (pr - cr) * mur, k = ck + (pk - ck) * muk, v = cv + (pv - cv) * muv; pr = cr; pk = ck; pv = cv;
;             const float wl = *(const LAS float*)(L + L_WL + (t * 65 + ch) * 4), al = *(const LAS float*)(L + L_AL + (t * 65 + ch) * 4), gl = *(const LAS float*)(L + L_GL + (t * 65 + ch) * 4);
;             const float z = -(w0 + wl); const float sp = fmaxf(z, 0.f) + __logf(1.f + __expf(-fabsf(z)));
;             const float lgd = -__expf(-sp - 0.5f);
;             const float ic = sigmoidf_(a0 + al);
;             const float kv = k * k_k; const float kq = k * (1.f + (ic - 1.f) * k_a);
;             kkv[tt] = kv; icv[tt] = ic; sq[tt] = kv * kv; bq[tt] = r * kq * r_k;
	v_pk_fma_f32 v[88:89], v[78:79], v[42:43], v[90:91] op_sel_hi:[1,0,1]
	v_pk_add_f32 v[78:79], v[82:83], -1.0 op_sel_hi:[1,0]
	ds_read_b32 v86, v123
	v_pk_fma_f32 v[78:79], v[46:47], v[78:79], 1.0 op_sel_hi:[0,1,0]
	v_pk_mul_f32 v[78:79], v[88:89], v[78:79]
	s_nop 0
	v_mul_f32_e32 v92, v175, v78
	v_mul_f32_e32 v187, v103, v92
	v_mul_f32_e32 v92, v178, v79
	v_mul_f32_e32 v186, v103, v92

; #define LAS __attribute__((address_space(3)))
; __device__ __forceinline__ void rwkv_chunk_group(Frame& F, int bc, unsigned long long& tsub) {
;     ...
;             const float wl = *(const LAS float*)(L + L_WL + (t * 65 + ch) * 4), al = *(const LAS float*)(L + L_AL + (t * 65 + ch) * 4), gl = *(const LAS float*)(L + L_GL + (t * 65 + ch) * 4);
;             const float z = -(w0 + wl); const float sp = fmaxf(z, 0.f) + __logf(1.f + __expf(-fabsf(z)));
	ds_read_b32 v92, v123 offset:16640
	s_waitcnt lgkmcnt(1)
	v_add_f32_e32 v86, v45, v86
	v_max_f32_e64 v93, -v86, 0
	v_mul_f32_e64 v86, |v86|, s1
	v_exp_f32_e32 v86, v86
	s_nop 0
	v_add_f32_e32 v86, 1.0, v86

; __device__ __forceinline__ void rwkv_chunk_group(Frame& F, int bc, unsigned long long& tsub) {
;     ...
;             const float z = -(w0 + wl); const float sp = fmaxf(z, 0.f) + __logf(1.f + __expf(-fabsf(z)));
	s_nop 1


; __device__ __forceinline__ void rwkv_chunk_group(Frame& F, int bc, unsigned long long& tsub) {
;     ...
;             const float z = -(w0 + wl); const float sp = fmaxf(z, 0.f) + __logf(1.f + __expf(-fabsf(z)));
	v_log_f32_e32 v86, v86
	s_nop 0
	v_mul_f32_e32 v94, 0x3f317217, v86
	v_fma_f32 v94, v86, s9, -v94
	v_fmac_f32_e32 v94, 0x3377d1cf, v86
	v_fmac_f32_e32 v94, 0x3f317217, v86

; __device__ __forceinline__ void rwkv_chunk_group(Frame& F, int bc, unsigned long long& tsub) {
;     ...
;             const float z = -(w0 + wl); const float sp = fmaxf(z, 0.f) + __logf(1.f + __expf(-fabsf(z)));
	s_nop 1
	v_mov_b32_e32 v86, v94


; #define LAS __attribute__((address_space(3)))
; __device__ __forceinline__ void rwkv_chunk_group(Frame& F, int bc, unsigned long long& tsub) {
;     ...
;             const float r = cr + (pr - cr) * mur, k = ck + (pk - ck) * muk, v = cv + (pv - cv) * muv; pr = cr; pk = ck; pv = cv;
;             const float wl = *(const LAS float*)(L + L_WL + (t * 65 + ch) * 4), al = *(const LAS float*)(L + L_AL + (t * 65 + ch) * 4), gl = *(const LAS float*)(L + L_GL + (t * 65 + ch) * 4);
	v_lshlrev_b32_e32 v94, 16, v159
	v_sub_f32_e32 v87, v87, v94
	v_fma_f32 v183, v87, v95, v94

; #define LAS __attribute__((address_space(3)))
; __device__ __forceinline__ float sigmoidf_(float x) { return __builtin_amdgcn_rcpf(1.0f + __expf(-x)); }
; __device__ __forceinline__ void rwkv_chunk_group(Frame& F, int bc, unsigned long long& tsub) {
;     ...
;             const float wl = *(const LAS float*)(L + L_WL + (t * 65 + ch) * 4), al = *(const LAS float*)(L + L_AL + (t * 65 + ch) * 4), gl = *(const LAS float*)(L + L_GL + (t * 65 + ch) * 4);
;             const float z = -(w0 + wl); const float sp = fmaxf(z, 0.f) + __logf(1.f + __expf(-fabsf(z)));
;             const float lgd = -__expf(-sp - 0.5f);
;             const float ic = sigmoidf_(a0 + al);
	ds_read_b32 v87, v124
	v_add_f32_e32 v86, v93, v86
	v_sub_f32_e32 v86, -0.5, v86
	v_mul_f32_e32 v86, 0x3fb8aa3b, v86
	v_exp_f32_e32 v93, v86
	s_waitcnt lgkmcnt(0)
	v_add_f32_e32 v87, v45, v87
	v_max_f32_e64 v97, -v87, 0
	v_mul_f32_e64 v87, |v87|, s1
	v_exp_f32_e32 v87, v87
	v_add_f32_e32 v86, v43, v92
	v_mul_f32_e32 v86, 0xbfb8aa3b, v86
	v_exp_f32_e32 v86, v86
	v_add_f32_e32 v87, 1.0, v87

; __device__ __forceinline__ float sigmoidf_(float x) { return __builtin_amdgcn_rcpf(1.0f + __expf(-x)); }
; __device__ __forceinline__ void rwkv_chunk_group(Frame& F, int bc, unsigned long long& tsub) {
;     ...
;             const float z = -(w0 + wl); const float sp = fmaxf(z, 0.f) + __logf(1.f + __expf(-fabsf(z)));
;             const float lgd = -__expf(-sp - 0.5f);
;             const float ic = sigmoidf_(a0 + al);
;             const float kv = k * k_k; const float kq = k * (1.f + (ic - 1.f) * k_a);
;             kkv[tt] = kv; icv[tt] = ic; sq[tt] = kv * kv; bq[tt] = r * kq * r_k;
;             rr[tt] = r; kp[tt] = kq; vv[tt] = v; run += lgd; ld[tt] = run; ggv[tt] = gl;
	v_sub_f32_e32 v184, v181, v93
	v_add_f32_e32 v86, 1.0, v86


; #define LAS __attribute__((address_space(3)))
; __device__ __forceinline__ float sigmoidf_(float x) { return __builtin_amdgcn_rcpf(1.0f + __expf(-x)); }
; __device__ __forceinline__ void rwkv_chunk_group(Frame& F, int bc, unsigned long long& tsub) {
;     ...
;             const float cr = bf2f(raw[tt + 1][0]), ck = bf2f(raw[tt + 1][1]), cv = bf2f(raw[tt + 1][2]);
;             const float r = cr + (pr - cr) * mur, k = ck + (pk - ck) * muk, v = cv + (pv - cv) * muv; pr = cr; pk = ck; pv = cv;
;             const float wl = *(const LAS float*)(L + L_WL + (t * 65 + ch) * 4), al = *(const LAS float*)(L + L_AL + (t * 65 + ch) * 4), gl = *(const LAS float*)(L + L_GL + (t * 65 + ch) * 4);
;             const float z = -(w0 + wl); const float sp = fmaxf(z, 0.f) + __logf(1.f + __expf(-fabsf(z)));
;             const float lgd = -__expf(-sp - 0.5f);
;             const float ic = sigmoidf_(a0 + al);
	v_log_f32_e32 v87, v87
	v_rcp_f32_e32 v86, v86
	v_sub_f32_e32 v94, v94, v197
	v_and_b32_e32 v93, 0xffff0000, v171
	v_mul_f32_e32 v98, 0x3f317217, v87
	v_fma_f32 v98, v87, s9, -v98
	v_fmac_f32_e32 v98, 0x3377d1cf, v87
	v_fmac_f32_e32 v98, 0x3f317217, v87

; __device__ __forceinline__ void rwkv_chunk_group(Frame& F, int bc, unsigned long long& tsub) {
;     ...
;             const float cr = bf2f(raw[tt + 1][0]), ck = bf2f(raw[tt + 1][1]), cv = bf2f(raw[tt + 1][2]);
;             const float r = cr + (pr - cr) * mur, k = ck + (pk - ck) * muk, v = cv + (pv - cv) * muv; pr = cr; pk = ck; pv = cv;
	v_lshlrev_b32_e32 v92, 16, v171
	v_pk_mov_b32 v[84:85], v[84:85], v[92:93] op_sel:[1,0]
	v_mov_b32_e32 v87, v98


; #define LAS __attribute__((address_space(3)))
; __device__ __forceinline__ float sigmoidf_(float x) { return __builtin_amdgcn_rcpf(1.0f + __expf(-x)); }
; __device__ __forceinline__ void rwkv_chunk_group(Frame& F, int bc, unsigned long long& tsub) {
;     ...
;             const float cr = bf2f(raw[tt + 1][0]), ck = bf2f(raw[tt + 1][1]), cv = bf2f(raw[tt + 1][2]);
;             const float r = cr + (pr - cr) * mur, k = ck + (pk - ck) * muk, v = cv + (pv - cv) * muv; pr = cr; pk = ck; pv = cv;
;             const float wl = *(const LAS float*)(L + L_WL + (t * 65 + ch) * 4), al = *(const LAS float*)(L + L_AL + (t * 65 + ch) * 4), gl = *(const LAS float*)(L + L_GL + (t * 65 + ch) * 4);
;             const float z = -(w0 + wl); const float sp = fmaxf(z, 0.f) + __logf(1.f + __expf(-fabsf(z)));
;             const float lgd = -__expf(-sp - 0.5f);
;             const float ic = sigmoidf_(a0 + al);
;             const float kv = k * k_k; const float kq = k * (1.f + (ic - 1.f) * k_a);
;             kkv[tt] = kv; icv[tt] = ic; sq[tt] = kv * kv; bq[tt] = r * kq * r_k;
	v_add_f32_e32 v87, v97, v87
	v_sub_f32_e32 v87, -0.5, v87
	v_mul_f32_e32 v87, 0x3fb8aa3b, v87
	v_exp_f32_e32 v188, v87
	v_add_f32_e32 v87, v43, v96
	v_mul_f32_e32 v87, 0xbfb8aa3b, v87
	v_exp_f32_e32 v87, v87
	v_and_b32_e32 v97, 0xffff0000, v170
	v_lshlrev_b32_e32 v96, 16, v170
	v_pk_mov_b32 v[90:91], v[90:91], v[96:97] op_sel:[1,0]
	v_add_f32_e32 v87, 1.0, v87
	v_rcp_f32_e32 v87, v87
	v_pk_add_f32 v[90:91], v[90:91], v[96:97] neg_lo:[0,1] neg_hi:[0,1]
	v_pk_add_f32 v[84:85], v[84:85], v[92:93] neg_lo:[0,1] neg_hi:[0,1]
	v_pk_fma_f32 v[98:99], v[90:91], v[42:43], v[96:97] op_sel_hi:[1,0,1]
	v_pk_add_f32 v[90:91], v[86:87], -1.0 op_sel_hi:[1,0]
	v_pk_fma_f32 v[84:85], v[84:85], v[52:53], v[92:93] op_sel_hi:[1,0,1]
	v_pk_fma_f32 v[90:91], v[46:47], v[90:91], 1.0 op_sel_hi:[0,1,0]
	v_pk_mul_f32 v[90:91], v[98:99], v[90:91]
	s_nop 0
	v_mul_f32_e32 v190, v180, v90
	v_mul_f32_e32 v196, v103, v190
	v_mul_f32_e32 v190, v183, v91
	v_mul_f32_e32 v195, v103, v190
	v_sub_f32_e32 v190, v184, v188
	v_fma_f32 v188, v94, v95, v197

; #define LAS __attribute__((address_space(3)))
; __device__ __forceinline__ float swap32_add(float a, float b) { auto rr = __builtin_amdgcn_permlane32_swap(__float_as_uint(a), __float_as_uint(b), false, false); return __uint_as_float(rr[0]) + __uint_as_float(rr[1]); }
; __device__ __forceinline__ void wave_sum8(float (&x)[8]) {
;     const float y0 = swap32_add(x[0], x[4]), y1 = swap32_add(x[1], x[5]), y2 = swap32_add(x[2], x[6]), y3 = swap32_add(x[3], x[7]);
; __device__ __forceinline__ void rwkv_chunk_group(Frame& F, int bc, unsigned long long& tsub) {
;     ...
;             const float wl = *(const LAS float*)(L + L_WL + (t * 65 + ch) * 4), al = *(const LAS float*)(L + L_AL + (t * 65 + ch) * 4), gl = *(const LAS float*)(L + L_GL + (t * 65 + ch) * 4);
;             const float z = -(w0 + wl); const float sp = fmaxf(z, 0.f) + __logf(1.f + __expf(-fabsf(z)));
	ds_read_b32 v94, v125
	v_permlane32_swap_b32_e32 v101, v196
	v_permlane32_swap_b32_e32 v100, v195
	s_waitcnt lgkmcnt(0)
	v_add_f32_e32 v94, v45, v94
	v_max_f32_e64 v192, -v94, 0
	v_mul_f32_e64 v94, |v94|, s1
	v_exp_f32_e32 v94, v94
	v_add_f32_e32 v201, v101, v196
	v_add_f32_e32 v195, v100, v195
	v_add_f32_e32 v94, 1.0, v94

; __device__ __forceinline__ void rwkv_chunk_group(Frame& F, int bc, unsigned long long& tsub) {
;     ...
;             const float z = -(w0 + wl); const float sp = fmaxf(z, 0.f) + __logf(1.f + __expf(-fabsf(z)));
	s_nop 1


; __device__ __forceinline__ void rwkv_chunk_group(Frame& F, int bc, unsigned long long& tsub) {
;     ...
;             const float z = -(w0 + wl); const float sp = fmaxf(z, 0.f) + __logf(1.f + __expf(-fabsf(z)));
	v_log_f32_e32 v94, v94
	s_nop 0
	v_mul_f32_e32 v198, 0x3f317217, v94
	v_fma_f32 v198, v94, s9, -v198
	v_fmac_f32_e32 v198, 0x3377d1cf, v94
	v_fmac_f32_e32 v198, 0x3f317217, v94

; __device__ __forceinline__ void rwkv_chunk_group(Frame& F, int bc, unsigned long long& tsub) {
;     ...
;             const float z = -(w0 + wl); const float sp = fmaxf(z, 0.f) + __logf(1.f + __expf(-fabsf(z)));
	s_nop 1
	v_mov_b32_e32 v94, v198


; #define LAS __attribute__((address_space(3)))
; __device__ __forceinline__ void rwkv_chunk_group(Frame& F, int bc, unsigned long long& tsub) {
;     ...
;             const float cr = bf2f(raw[tt + 1][0]), ck = bf2f(raw[tt + 1][1]), cv = bf2f(raw[tt + 1][2]);
;             const float r = cr + (pr - cr) * mur, k = ck + (pk - ck) * muk, v = cv + (pv - cv) * muv; pr = cr; pk = ck; pv = cv;
;             const float wl = *(const LAS float*)(L + L_WL + (t * 65 + ch) * 4), al = *(const LAS float*)(L + L_AL + (t * 65 + ch) * 4), gl = *(const LAS float*)(L + L_GL + (t * 65 + ch) * 4);
;             const float z = -(w0 + wl); const float sp = fmaxf(z, 0.f) + __logf(1.f + __expf(-fabsf(z)));
;             const float lgd = -__expf(-sp - 0.5f);
	v_lshlrev_b32_e32 v198, 16, v172
	v_pk_mov_b32 v[92:93], v[92:93], v[198:199] op_sel:[1,0]
	v_add_f32_e32 v94, v192, v94
	v_pk_add_f32 v[92:93], v[92:93], v[198:199] neg_lo:[0,1] neg_hi:[0,1]
	v_sub_f32_e32 v94, -0.5, v94
	v_pk_fma_f32 v[92:93], v[92:93], v[52:53], v[198:199] op_sel_hi:[1,0,1]

; #define LAS __attribute__((address_space(3)))
; __device__ __forceinline__ float sigmoidf_(float x) { return __builtin_amdgcn_rcpf(1.0f + __expf(-x)); }
; __device__ __forceinline__ void rwkv_chunk_group(Frame& F, int bc, unsigned long long& tsub) {
;     ...
;             const float r = cr + (pr - cr) * mur, k = ck + (pk - ck) * muk, v = cv + (pv - cv) * muv; pr = cr; pk = ck; pv = cv;
;             const float wl = *(const LAS float*)(L + L_WL + (t * 65 + ch) * 4), al = *(const LAS float*)(L + L_AL + (t * 65 + ch) * 4), gl = *(const LAS float*)(L + L_GL + (t * 65 + ch) * 4);
;             const float z = -(w0 + wl); const float sp = fmaxf(z, 0.f) + __logf(1.f + __expf(-fabsf(z)));
;             const float lgd = -__expf(-sp - 0.5f);
;             const float ic = sigmoidf_(a0 + al);
	ds_read_b32 v52, v126
	v_mul_f32_e32 v94, 0x3fb8aa3b, v94
	v_exp_f32_e32 v192, v94
	v_add_f32_e32 v94, v43, v191
	v_lshlrev_b32_e32 v191, 16, v163
	v_sub_f32_e32 v197, v197, v191
	v_fmac_f32_e32 v191, v197, v95


; #define LAS __attribute__((address_space(3)))
; __device__ __forceinline__ float sigmoidf_(float x) { return __builtin_amdgcn_rcpf(1.0f + __expf(-x)); }
; __device__ __forceinline__ void rwkv_chunk_group(Frame& F, int bc, unsigned long long& tsub) {
;     ...
;             const float wl = *(const LAS float*)(L + L_WL + (t * 65 + ch) * 4), al = *(const LAS float*)(L + L_AL + (t * 65 + ch) * 4), gl = *(const LAS float*)(L + L_GL + (t * 65 + ch) * 4);
;             const float z = -(w0 + wl); const float sp = fmaxf(z, 0.f) + __logf(1.f + __expf(-fabsf(z)));
;             const float lgd = -__expf(-sp - 0.5f);
;             const float ic = sigmoidf_(a0 + al);
	ds_read_b32 v95, v126 offset:16640
	ds_read_b32 v200, v126 offset:33280
	s_waitcnt lgkmcnt(2)
	v_add_f32_e32 v45, v45, v52
	v_max_f32_e64 v52, -v45, 0
	v_mul_f32_e64 v45, |v45|, s1
	v_exp_f32_e32 v45, v45
	s_waitcnt lgkmcnt(1)
	v_add_f32_e32 v43, v43, v95
	v_mul_f32_e32 v94, 0xbfb8aa3b, v94
	v_mul_f32_e32 v43, 0xbfb8aa3b, v43
	v_add_f32_e32 v45, 1.0, v45

; __device__ __forceinline__ float sigmoidf_(float x) { return __builtin_amdgcn_rcpf(1.0f + __expf(-x)); }
; __device__ __forceinline__ void rwkv_chunk_group(Frame& F, int bc, unsigned long long& tsub) {
;     ...
;             const float z = -(w0 + wl); const float sp = fmaxf(z, 0.f) + __logf(1.f + __expf(-fabsf(z)));
;             const float lgd = -__expf(-sp - 0.5f);
;             const float ic = sigmoidf_(a0 + al);
	v_exp_f32_e32 v94, v94
	v_exp_f32_e32 v43, v43


; __device__ __forceinline__ float sigmoidf_(float x) { return __builtin_amdgcn_rcpf(1.0f + __expf(-x)); }
; __device__ __forceinline__ void rwkv_chunk_group(Frame& F, int bc, unsigned long long& tsub) {
;     ...
;             const float z = -(w0 + wl); const float sp = fmaxf(z, 0.f) + __logf(1.f + __expf(-fabsf(z)));
;             const float lgd = -__expf(-sp - 0.5f);
;             const float ic = sigmoidf_(a0 + al);
	v_log_f32_e32 v45, v45
	v_add_f32_e32 v94, 1.0, v94
	v_add_f32_e32 v43, 1.0, v43
	v_rcp_f32_e32 v94, v94
	v_mul_f32_e32 v197, 0x3f317217, v45
	v_fma_f32 v197, v45, s9, -v197
	v_fmac_f32_e32 v197, 0x3377d1cf, v45
	v_fmac_f32_e32 v197, 0x3f317217, v45

; __device__ __forceinline__ float sigmoidf_(float x) { return __builtin_amdgcn_rcpf(1.0f + __expf(-x)); }
; __device__ __forceinline__ void rwkv_chunk_group(Frame& F, int bc, unsigned long long& tsub) {
;     ...
;             const float z = -(w0 + wl); const float sp = fmaxf(z, 0.f) + __logf(1.f + __expf(-fabsf(z)));
;             const float lgd = -__expf(-sp - 0.5f);
;             const float ic = sigmoidf_(a0 + al);
;             const float kv = k * k_k; const float kq = k * (1.f + (ic - 1.f) * k_a);
;             kkv[tt] = kv; icv[tt] = ic; sq[tt] = kv * kv; bq[tt] = r * kq * r_k;
;             rr[tt] = r; kp[tt] = kq; vv[tt] = v; run += lgd; ld[tt] = run; ggv[tt] = gl;
	v_rcp_f32_e32 v95, v43
	v_sub_f32_e32 v192, v190, v192
	v_mov_b32_e32 v45, v197


; __device__ __forceinline__ void wave_sum8(float (&x)[8]) {
;     const float y0 = swap32_add(x[0], x[4]), y1 = swap32_add(x[1], x[5]), y2 = swap32_add(x[2], x[6]), y3 = swap32_add(x[3], x[7]);
;     float z0 = swap16_add(y0, y2), z1 = swap16_add(y1, y3);
;     z0 = dpp_add(z0, 0); z1 = dpp_add(z1, 0); z0 = dpp_add(z0, 1); z1 = dpp_add(z1, 1); z0 = dpp_add(z0, 2); z1 = dpp_add(z1, 2); z0 = dpp_add(z0, 3); z1 = dpp_add(z1, 3);
;     const int i0 = __builtin_bit_cast(int, z0), i1 = __builtin_bit_cast(int, z1);
;     x[0] = __builtin_bit_cast(float, __builtin_amdgcn_readlane(i0, 0));  x[2] = __builtin_bit_cast(float, __builtin_amdgcn_readlane(i0, 16));
;     x[4] = __builtin_bit_cast(float, __builtin_amdgcn_readlane(i0, 32)); x[6] = __builtin_bit_cast(float, __builtin_amdgcn_readlane(i0, 48));
;     x[1] = __builtin_bit_cast(float, __builtin_amdgcn_readlane(i1, 0));  x[3] = __builtin_bit_cast(float, __builtin_amdgcn_readlane(i1, 16));
;     x[5] = __builtin_bit_cast(float, __builtin_amdgcn_readlane(i1, 32)); x[7] = __builtin_bit_cast(float, __builtin_amdgcn_readlane(i1, 48));
; }
; __device__ __forceinline__ void rwkv_chunk_group(Frame& F, int bc, unsigned long long& tsub) {
;     ...
;             const float kv = k * k_k; const float kq = k * (1.f + (ic - 1.f) * k_a);
;             kkv[tt] = kv; icv[tt] = ic; sq[tt] = kv * kv; bq[tt] = r * kq * r_k;
;             rr[tt] = r; kp[tt] = kq; vv[tt] = v; run += lgd; ld[tt] = run; ggv[tt] = gl;
;         }
;         wave_sum8(sq); wave_sum8(bq);
; #pragma unroll
;         for (int tt = 0; tt < 8; ++tt) { const float kn = kkv[tt] * __builtin_amdgcn_rsqf(fmaxf(sq[tt], 1e-24f));
;             aa[tt] = -kn; bb[tt] = kn * icv[tt]; vbv[tt] = bq[tt] * vv[tt]; }
;         *(LAS float*)(L + L_GT + (w * 64 + ch) * 4) = run;
;         *(GAS v4u*)(VBp + ch * 64 + tb) = (v4u){pk2(vbv[0], vbv[1]), pk2(vbv[2], vbv[3]), pk2(vbv[4], vbv[5]), pk2(vbv[6], vbv[7])};
;         *(GAS v4u*)(Gp + ch * 64 + tb) = (v4u){pk2(ggv[0], ggv[1]), pk2(ggv[2], ggv[3]), pk2(ggv[4], ggv[5]), pk2(ggv[6], ggv[7])};
;         if (hh + 1 < RW_H) {
;             const bool has = (c * CH + tb > 0);
; #pragma unroll
;             for (int tt = 0; tt < 9; ++tt) { const size_t off = (size_t)(row0 + tb + tt - 1) * PRW + hnext * 64 + ch;
;                 if (tt > 0 || has) { raw[tt][0] = P[off]; raw[tt][1] = P[off + 512]; raw[tt][2] = P[off + 1024]; } }
	v_add_f32_e32 v45, v52, v45
	v_sub_f32_e32 v45, -0.5, v45
	v_mul_f32_e32 v45, 0x3fb8aa3b, v45
	v_exp_f32_e32 v45, v45
	s_nop 0
	v_pk_mul_f32 v[100:101], v[80:81], v[44:45] op_sel_hi:[1,0]
	v_pk_mul_f32 v[80:81], v[98:99], v[44:45] op_sel_hi:[1,0]
	v_pk_mul_f32 v[196:197], v[100:101], v[100:101]
	v_pk_mul_f32 v[98:99], v[80:81], v[80:81]
	v_sub_f32_e32 v52, v192, v45
	s_nop 0
	v_permlane32_swap_b32_e32 v196, v98
	v_permlane32_swap_b32_e32 v197, v99
	v_add_f32_e32 v196, v196, v98
	v_add_f32_e32 v197, v197, v99
	v_lshlrev_b32_e32 v98, 16, v165
	v_and_b32_e32 v99, 0xffff0000, v165
	v_pk_mov_b32 v[96:97], v[96:97], v[98:99] op_sel:[1,0]
	v_pk_mul_f32 v[88:89], v[88:89], v[44:45] op_sel_hi:[1,0]
	v_pk_add_f32 v[96:97], v[96:97], v[98:99] neg_lo:[0,1] neg_hi:[0,1]
	v_pk_mul_f32 v[198:199], v[88:89], v[88:89]
	v_pk_fma_f32 v[42:43], v[96:97], v[42:43], v[98:99] op_sel_hi:[1,0,1]
	v_pk_add_f32 v[98:99], v[94:95], -1.0 op_sel_hi:[1,0]
	v_pk_mul_f32 v[44:45], v[42:43], v[44:45] op_sel_hi:[1,0]
	v_pk_fma_f32 v[98:99], v[46:47], v[98:99], 1.0 op_sel_hi:[0,1,0]
	v_pk_mul_f32 v[42:43], v[42:43], v[98:99]
	v_pk_mul_f32 v[96:97], v[44:45], v[44:45]
	v_mul_f32_e32 v46, v188, v42
	v_mul_f32_e32 v46, v103, v46
	s_nop 1
	v_permlane32_swap_b32_e32 v187, v46
	v_add_f32_e32 v46, v187, v46
	v_mul_f32_e32 v98, v191, v43
	s_nop 0
	v_permlane16_swap_b32_e32 v201, v46
	v_mul_f32_e32 v98, v103, v98
	v_add_f32_e32 v46, v201, v46
	s_nop 0
	v_permlane32_swap_b32_e32 v186, v98
	v_add_f32_dpp v46, v46, v46 quad_perm:[1,0,3,2] row_mask:0xf bank_mask:0xf bound_ctrl:1
	v_add_f32_e32 v98, v186, v98
	s_nop 1
	v_permlane16_swap_b32_e32 v195, v98
	v_add_f32_dpp v46, v46, v46 quad_perm:[2,3,0,1] row_mask:0xf bank_mask:0xf bound_ctrl:1
	v_add_f32_e32 v98, v195, v98
	v_permlane32_swap_b32_e32 v198, v96
	v_add_f32_dpp v46, v46, v46 row_half_mirror row_mask:0xf bank_mask:0xf bound_ctrl:1
	v_permlane32_swap_b32_e32 v199, v97
	s_nop 0
	v_add_f32_dpp v46, v46, v46 row_mirror row_mask:0xf bank_mask:0xf bound_ctrl:1
	v_add_f32_dpp v98, v98, v98 quad_perm:[1,0,3,2] row_mask:0xf bank_mask:0xf bound_ctrl:1
	v_readlane_b32 s14, v46, 0
	v_readlane_b32 s64, v46, 16
	v_readlane_b32 s72, v46, 32
	v_readlane_b32 s96, v46, 48
	v_add_f32_e32 v46, v198, v96
	v_add_f32_e32 v96, v199, v97
	v_add_f32_dpp v98, v98, v98 quad_perm:[2,3,0,1] row_mask:0xf bank_mask:0xf bound_ctrl:1
	v_permlane16_swap_b32_e32 v196, v46
	v_permlane16_swap_b32_e32 v197, v96
	v_add_f32_dpp v98, v98, v98 row_half_mirror row_mask:0xf bank_mask:0xf bound_ctrl:1
	v_add_f32_e32 v46, v196, v46
	v_add_f32_e32 v96, v197, v96
	v_add_f32_dpp v98, v98, v98 row_mirror row_mask:0xf bank_mask:0xf bound_ctrl:1
	v_add_f32_dpp v46, v46, v46 quad_perm:[1,0,3,2] row_mask:0xf bank_mask:0xf bound_ctrl:1
	v_add_f32_dpp v96, v96, v96 quad_perm:[1,0,3,2] row_mask:0xf bank_mask:0xf bound_ctrl:1
	v_readlane_b32 s73, v98, 32
	v_add_f32_dpp v46, v46, v46 quad_perm:[2,3,0,1] row_mask:0xf bank_mask:0xf bound_ctrl:1
	v_add_f32_dpp v96, v96, v96 quad_perm:[2,3,0,1] row_mask:0xf bank_mask:0xf bound_ctrl:1
	v_readlane_b32 s15, v98, 0
	v_readlane_b32 s65, v98, 16
	v_readlane_b32 s97, v98, 48
	v_add_f32_dpp v46, v46, v46 row_half_mirror row_mask:0xf bank_mask:0xf bound_ctrl:1
	v_add_f32_dpp v96, v96, v96 row_half_mirror row_mask:0xf bank_mask:0xf bound_ctrl:1
	v_pk_mul_f32 v[196:197], v[84:85], s[72:73]
	s_lshl_b64 s[72:73], s[66:67], 13
	v_pk_mul_f32 v[98:99], v[36:37], s[14:15]
	v_pk_mul_f32 v[186:187], v[76:77], s[64:65]
	v_add_f32_dpp v46, v46, v46 row_mirror row_mask:0xf bank_mask:0xf bound_ctrl:1
	v_add_f32_dpp v96, v96, v96 row_mirror row_mask:0xf bank_mask:0xf bound_ctrl:1
	v_pk_mul_f32 v[198:199], v[92:93], s[96:97]
	v_readlane_b32 s15, v254, 39
	s_cmp_eq_u32 s68, 7
	v_readlane_b32 s93, v46, 0
	v_readlane_b32 s71, v46, 16
	v_readlane_b32 s69, v46, 32
	v_readlane_b32 s64, v46, 48
	v_readlane_b32 s14, v96, 0
	v_readlane_b32 s77, v96, 16
	v_readlane_b32 s70, v96, 32
	v_readlane_b32 s65, v96, 48
	v_add_u32_e32 v46, s15, v105
	v_cvt_pk_bf16_f32 v96, v98, v99
	v_cvt_pk_bf16_f32 v97, v186, v187
	v_cvt_pk_bf16_f32 v98, v196, v197
	v_cvt_pk_bf16_f32 v99, v198, v199
	v_lshl_add_u64 v[186:187], v[62:63], 0, s[72:73]
	s_cselect_b64 s[96:97], -1, 0
	ds_write_b32 v46, v52
	global_store_dwordx4 v[186:187], v[96:99], off
	s_and_b64 vcc, exec, s[96:97]
	s_nop 0
	v_cvt_pk_bf16_f32 v96, v47, v177
	v_cvt_pk_bf16_f32 v97, v182, v185
	v_cvt_pk_bf16_f32 v98, v189, v193
	s_waitcnt lgkmcnt(1)
	v_cvt_pk_bf16_f32 v99, v194, v200
	v_lshl_add_u64 v[46:47], v[64:65], 0, s[72:73]
	global_store_dwordx4 v[46:47], v[96:99], off
	s_cbranch_vccnz .LBB0_1416
	v_readlane_b32 s72, v254, 60
	s_lshl_b32 s94, s13, 7
	v_readlane_b32 s73, v254, 61
	v_lshl_add_u64 v[46:47], v[56:57], 0, s[94:95]
	s_andn2_b64 vcc, exec, s[72:73]
	s_cbranch_vccnz .LBB0_1415
	v_readlane_b32 s72, v254, 62
	v_readlane_b32 s73, v254, 63
	s_nop 1
	v_lshl_add_u64 v[96:97], v[46:47], 0, s[72:73]
	global_load_ushort v153, v[96:97], off
	global_load_ushort v202, v[96:97], off offset:1024
	global_load_ushort v215, v[96:97], off offset:2048
